# K-address xor toggles moved from step B (right before its ds_reads) to step A (right after its ds_reads)
# speedup vs baseline: 1.0026x; 1.0001x over previous
; #define SBAR() __builtin_amdgcn_sched_barrier(0)
; __device__ __forceinline__ unsigned cvtpk(float lo, float hi) { unsigned r; asm volatile("v_cvt_pk_bf16_f32 %0, %1, %2" : "=v"(r) : "v"(lo), "v"(hi)); return r; }
; __device__ __forceinline__ void qkt_fin(f32x16& n0, f32x16& n1, const bf16_t* Ks, const bf16x8* qr, const f32x16& negm, int r32, int hi, ...
;   float psa = 0.f, psb = 0.f; u32x4 wa, wb, wc, wd;
;     ...
; #pragma unroll
;   for (int d0 = 0; d0 < 8; ++d0) { int cb = (d0 * 16 + hi * 8) * 2;
;     bf16x8 b0 = *reinterpret_cast<const bf16x8*>((const char*)Ks + KSWZ(r32, cb));
;     bf16x8 b1 = *reinterpret_cast<const bf16x8*>((const char*)Ks + KSWZ(32 + r32, cb));
;     SBAR(); if (d0 == 0) n0 = __builtin_amdgcn_mfma_f32_32x32x16_bf16(b0, qr[0], negm, 0, 0, 0); else n0 = __builtin_amdgcn_mfma_f32_32x32x16_bf16(b0, qr[d0], n0, 0, 0, 0);
;     SBAR(); QF_CHUNK(2 * d0); SBAR();
;     if (d0 == 0) n1 = __builtin_amdgcn_mfma_f32_32x32x16_bf16(b1, qr[0], negm, 0, 0, 0); else n1 = __builtin_amdgcn_mfma_f32_32x32x16_bf16(b1, qr[d0], n1, 0, 0, 0);
;     SBAR(); QF_CHUNK(2 * d0 + 1); SBAR();
;     if (d0 == 7) { vf8_read<0>(vf0, vbv); SBAR(); } }
;     ...
;   psb += P1[15]; wd[3] = cvtpk(P1[14], P1[15]);
;   l_reg = l_reg * alpha + (psa + psb);
;   pa0 = *reinterpret_cast<bf16x8*>(&wa); pa1 = *reinterpret_cast<bf16x8*>(&wb); pa2 = *reinterpret_cast<bf16x8*>(&wc); pa3 = *reinterpret_cast<bf16x8*>(&wd);
; }
.LBB0_453:
	s_add_i32 s97, s96, 0xffff8000
	s_xor_b32 s98, s96, 0x10000
	s_add_i32 s99, s96, 0x8000
	s_and_b32 s99, s99, 0x18000
	ds_read_b128 v[98:101], v184 offset:49152
	ds_read_b128 v[196:199], v184 offset:57344
	v_xor_b32_e32 v184, 0x10000, v184
	ds_read_b128 v[248:251], v185 offset:49152
	ds_read_b128 v[252:255], v185 offset:57344
	v_xor_b32_e32 v185, 0x10000, v185
	v_add_u32_e32 v0, s97, v235
	s_waitcnt lgkmcnt(3)
	v_mfma_f32_32x32x16_bf16 v[132:147], v[98:101], v[152:155], v[66:81]
	v_exp_f32_e32 v82, v82
	s_waitcnt lgkmcnt(2)
	v_mfma_f32_32x32x16_bf16 v[98:113], v[196:199], v[152:155], v[66:81]
	v_exp_f32_e32 v83, v83
	v_add_f32_e32 v245, v115, v114
	v_cvt_pk_bf16_f32 v196, v114, v115
	ds_read_b128 v[202:205], v186 offset:49152
	ds_read_b128 v[206:209], v186 offset:57344
	v_xor_b32_e32 v186, 0x10000, v186
	s_waitcnt lgkmcnt(3)
	v_mfma_f32_32x32x16_bf16 v[132:147], v[248:251], v[160:163], v[132:147]
	v_exp_f32_e32 v84, v84
	v_add_f32_e32 v245, v116, v245
	v_add_f32_e32 v246, v82, v83
	s_waitcnt lgkmcnt(2)
	v_mfma_f32_32x32x16_bf16 v[98:113], v[252:255], v[160:163], v[98:113]
	v_exp_f32_e32 v85, v85
	v_add_f32_e32 v245, v117, v245
	v_add_f32_e32 v246, v246, v84
	v_cvt_pk_bf16_f32 v197, v116, v117
	v_cvt_pk_bf16_f32 v200, v82, v83
	ds_read_b128 v[248:251], v187 offset:49152
	ds_read_b128 v[252:255], v187 offset:57344
	v_xor_b32_e32 v187, 0x10000, v187
	s_waitcnt lgkmcnt(3)
	v_mfma_f32_32x32x16_bf16 v[132:147], v[202:205], v[148:151], v[132:147]
	v_exp_f32_e32 v86, v86
	v_add_f32_e32 v245, v118, v245
	v_add_f32_e32 v246, v246, v85
	s_waitcnt lgkmcnt(2)
	v_mfma_f32_32x32x16_bf16 v[98:113], v[206:209], v[148:151], v[98:113]
	v_exp_f32_e32 v87, v87
	v_add_f32_e32 v245, v119, v245
	v_add_f32_e32 v246, v246, v86
	v_cvt_pk_bf16_f32 v198, v118, v119
	v_cvt_pk_bf16_f32 v201, v84, v85
	ds_read_b128 v[204:207], v188 offset:49152
	ds_read_b128 v[208:211], v188 offset:57344
	v_xor_b32_e32 v188, 0x10000, v188
	s_waitcnt lgkmcnt(3)
	v_mfma_f32_32x32x16_bf16 v[132:147], v[248:251], v[156:159], v[132:147]
	v_exp_f32_e32 v88, v88
	v_add_f32_e32 v245, v120, v245
	v_add_f32_e32 v246, v246, v87
	s_waitcnt lgkmcnt(2)
	v_mfma_f32_32x32x16_bf16 v[98:113], v[252:255], v[156:159], v[98:113]
	v_exp_f32_e32 v89, v89
	v_add_f32_e32 v245, v121, v245
	v_add_f32_e32 v246, v246, v88
	v_cvt_pk_bf16_f32 v199, v120, v121
	v_cvt_pk_bf16_f32 v202, v86, v87
	ds_read_b128 v[248:251], v189 offset:49152
	ds_read_b128 v[252:255], v189 offset:57344
	v_xor_b32_e32 v189, 0x10000, v189
	s_waitcnt lgkmcnt(3)
	v_mfma_f32_32x32x16_bf16 v[132:147], v[204:207], v[168:171], v[132:147]
	v_exp_f32_e32 v90, v90
	v_add_f32_e32 v245, v122, v245
	v_add_f32_e32 v246, v246, v89
	s_waitcnt lgkmcnt(2)
	v_mfma_f32_32x32x16_bf16 v[98:113], v[208:211], v[168:171], v[98:113]
	v_exp_f32_e32 v91, v91
	v_add_f32_e32 v245, v123, v245
	v_add_f32_e32 v246, v246, v90
	v_cvt_pk_bf16_f32 v204, v122, v123
	v_cvt_pk_bf16_f32 v203, v88, v89
	ds_read_b128 v[114:117], v190 offset:49152
	ds_read_b128 v[118:121], v190 offset:57344
	v_xor_b32_e32 v190, 0x10000, v190
	s_waitcnt lgkmcnt(3)
	v_mfma_f32_32x32x16_bf16 v[132:147], v[248:251], v[176:179], v[132:147]
	v_exp_f32_e32 v92, v92
	v_add_f32_e32 v245, v124, v245
	v_add_f32_e32 v246, v246, v91
	s_waitcnt lgkmcnt(2)
	v_mfma_f32_32x32x16_bf16 v[98:113], v[252:255], v[176:179], v[98:113]
	v_exp_f32_e32 v93, v93
	v_add_f32_e32 v245, v125, v245
	v_add_f32_e32 v246, v246, v92
	v_cvt_pk_bf16_f32 v205, v124, v125
	v_cvt_pk_bf16_f32 v208, v90, v91
	ds_read_b128 v[248:251], v191 offset:49152
	ds_read_b128 v[252:255], v191 offset:57344
	v_xor_b32_e32 v191, 0x10000, v191
	s_waitcnt lgkmcnt(3)
	v_mfma_f32_32x32x16_bf16 v[132:147], v[114:117], v[164:167], v[132:147]
	v_exp_f32_e32 v94, v94
	v_add_f32_e32 v245, v126, v245
	v_add_f32_e32 v246, v246, v93
	s_waitcnt lgkmcnt(2)
	v_mfma_f32_32x32x16_bf16 v[98:113], v[118:121], v[164:167], v[98:113]
	v_exp_f32_e32 v95, v95
	v_add_f32_e32 v245, v127, v245
	v_add_f32_e32 v246, v246, v94
	v_cvt_pk_bf16_f32 v206, v126, v127
	v_cvt_pk_bf16_f32 v209, v92, v93
	s_waitcnt lgkmcnt(1)
	v_mfma_f32_32x32x16_bf16 v[132:147], v[248:251], v[172:175], v[132:147]
	v_exp_f32_e32 v96, v96
	v_add_f32_e32 v245, v128, v245
	v_add_f32_e32 v246, v246, v95
	s_waitcnt lgkmcnt(0)
	v_mfma_f32_32x32x16_bf16 v[98:113], v[252:255], v[172:175], v[98:113]
	v_exp_f32_e32 v97, v97
	v_add_f32_e32 v245, v129, v245
	v_add_f32_e32 v246, v246, v96
	v_cvt_pk_bf16_f32 v207, v128, v129
	v_cvt_pk_bf16_f32 v210, v94, v95
	v_mov_b32_e32 v131, v97
	v_cvt_pk_bf16_f32 v211, v96, v97
	ds_read_b64_tr_b16 v[94:95], v0 offset:0
	ds_read_b64_tr_b16 v[96:97], v0 offset:2048
	ds_read_b64_tr_b16 v[90:91], v0 offset:4096
	ds_read_b64_tr_b16 v[92:93], v0 offset:6144
	ds_read_b64_tr_b16 v[86:87], v0 offset:8192
	ds_read_b64_tr_b16 v[88:89], v0 offset:10240
	ds_read_b64_tr_b16 v[82:83], v0 offset:12288
	ds_read_b64_tr_b16 v[84:85], v0 offset:14336
	s_andn2_b64 s[8:9], exec, s[0:1]
	s_andn2_b64 vcc, exec, s[0:1]
	s_cbranch_vccnz .LBB0_456
; template <bool FIRST, bool DOEXP = true>
; __device__ __forceinline__ void partialSM(f32x16& p0, f32x16& p1, float& m_reg, f32x16& negm, float& alpha, const bool track = true) {
;     ...
;   float pmax = p0[0];
; #pragma unroll
;   for (int r = 1; r < 16; ++r) pmax = fmaxf(pmax, p0[r]);
; #pragma unroll
;   for (int r = 0; r < 16; ++r) pmax = fmaxf(pmax, p1[r]);
;   { auto rr = __builtin_amdgcn_permlane32_swap(__float_as_uint(pmax), __float_as_uint(pmax), false, false);
;     pmax = fmaxf(__uint_as_float(rr[0]), __uint_as_float(rr[1])); }
;   if (!FIRST && __builtin_expect(__all(pmax <= THRL), 1)) { alpha = 1.f; }
;   else { const float dl = FIRST ? pmax : fmaxf(pmax, 0.f); m_reg += dl; alpha = FIRST ? 1.f : __builtin_amdgcn_exp2f(-dl);
; #pragma unroll
;     for (int r = 0; r < 16; ++r) { p0[r] -= dl; p1[r] -= dl; }
; #pragma unroll
;     for (int r = 0; r < 16; ++r) negm[r] = -m_reg;
;     asm volatile("" : "+v"(negm)); }
	v_max_f32_e32 v114, v132, v133
	v_max3_f32 v114, v114, v134, v135
	v_max3_f32 v114, v114, v136, v137
	v_max3_f32 v114, v114, v138, v139
	v_max3_f32 v114, v114, v140, v141
	v_max3_f32 v114, v114, v142, v143
	v_max3_f32 v114, v114, v144, v145
	v_max3_f32 v114, v114, v146, v147
	v_max3_f32 v114, v114, v98, v99
	v_max3_f32 v114, v114, v100, v101
	v_max3_f32 v114, v114, v102, v103
	v_max3_f32 v114, v114, v104, v105
	v_max3_f32 v114, v114, v106, v107
	v_max3_f32 v114, v114, v108, v109
	v_max3_f32 v114, v114, v110, v111
	v_max3_f32 v114, v114, v112, v113
	v_mov_b32_e32 v115, v114
	s_nop 1
	v_permlane32_swap_b32_e32 v114, v115
	v_max_f32_e32 v114, v114, v115
	v_cmp_ge_f32_e32 vcc, s69, v114
	s_cmp_eq_u64 vcc, exec
	v_mov_b32_e32 v130, 1.0
	s_cbranch_scc1 .LBB0_457
	v_max_f32_e32 v66, v114, v114
	v_max_f32_e32 v66, 0, v66
	v_exp_f32_e64 v130, -v66
	v_add_f32_e32 v222, v222, v66
	v_sub_f32_e32 v147, v147, v66
	v_sub_f32_e32 v146, v146, v66
	v_sub_f32_e32 v145, v145, v66
	v_sub_f32_e32 v144, v144, v66
	v_sub_f32_e32 v143, v143, v66
	v_sub_f32_e32 v142, v142, v66
	v_sub_f32_e32 v141, v141, v66
	v_sub_f32_e32 v140, v140, v66
	v_sub_f32_e32 v139, v139, v66
	v_sub_f32_e32 v138, v138, v66
	v_sub_f32_e32 v137, v137, v66
	v_sub_f32_e32 v136, v136, v66
	v_sub_f32_e32 v135, v135, v66
	v_sub_f32_e32 v134, v134, v66
	v_sub_f32_e32 v133, v133, v66
	v_sub_f32_e32 v132, v132, v66
	v_sub_f32_e32 v113, v113, v66
	v_sub_f32_e32 v112, v112, v66
	v_sub_f32_e32 v111, v111, v66
	v_sub_f32_e32 v110, v110, v66
	v_sub_f32_e32 v109, v109, v66
	v_sub_f32_e32 v108, v108, v66
	v_sub_f32_e32 v107, v107, v66
	v_sub_f32_e32 v106, v106, v66
	v_sub_f32_e32 v105, v105, v66
	v_sub_f32_e32 v104, v104, v66
	v_sub_f32_e32 v103, v103, v66
	v_sub_f32_e32 v102, v102, v66
	v_sub_f32_e32 v101, v101, v66
	v_sub_f32_e32 v100, v100, v66
	v_sub_f32_e32 v99, v99, v66
	v_sub_f32_e32 v98, v98, v66
	v_xor_b32_e32 v66, 0x80000000, v222
	v_mov_b32_e32 v67, v66
	v_mov_b32_e32 v68, v66
	v_mov_b32_e32 v69, v66
	v_mov_b32_e32 v70, v66
	v_mov_b32_e32 v71, v66
	v_mov_b32_e32 v72, v66
	v_mov_b32_e32 v73, v66
	v_mov_b32_e32 v74, v66
	v_mov_b32_e32 v75, v66
	v_mov_b32_e32 v76, v66
	v_mov_b32_e32 v77, v66
	v_mov_b32_e32 v78, v66
	v_mov_b32_e32 v79, v66
	v_mov_b32_e32 v80, v66
	v_mov_b32_e32 v81, v66
	s_branch .LBB0_457

; #define SBAR() __builtin_amdgcn_sched_barrier(0)
; __device__ __forceinline__ unsigned cvtpk(float lo, float hi) { unsigned r; asm volatile("v_cvt_pk_bf16_f32 %0, %1, %2" : "=v"(r) : "v"(lo), "v"(hi)); return r; }
; template <bool FIRST, bool DOEXP = true>
; __device__ __forceinline__ void partialSM(f32x16& p0, f32x16& p1, float& m_reg, f32x16& negm, float& alpha, const bool track = true) {
;     ...
;   float pmax = p0[0];
; #pragma unroll
;   for (int r = 1; r < 16; ++r) pmax = fmaxf(pmax, p0[r]);
; #pragma unroll
;   for (int r = 0; r < 16; ++r) pmax = fmaxf(pmax, p1[r]);
;   { auto rr = __builtin_amdgcn_permlane32_swap(__float_as_uint(pmax), __float_as_uint(pmax), false, false);
;     pmax = fmaxf(__uint_as_float(rr[0]), __uint_as_float(rr[1])); }
;   if (!FIRST && __builtin_expect(__all(pmax <= THRL), 1)) { alpha = 1.f; }
; __device__ __forceinline__ void qkt_fin(f32x16& n0, f32x16& n1, const bf16_t* Ks, const bf16x8* qr, const f32x16& negm, int r32, int hi, ...
;   float psa = 0.f, psb = 0.f; u32x4 wa, wb, wc, wd;
;     ...
; #pragma unroll
;   for (int d0 = 0; d0 < 8; ++d0) { int cb = (d0 * 16 + hi * 8) * 2;
;     bf16x8 b0 = *reinterpret_cast<const bf16x8*>((const char*)Ks + KSWZ(r32, cb));
;     bf16x8 b1 = *reinterpret_cast<const bf16x8*>((const char*)Ks + KSWZ(32 + r32, cb));
;     SBAR(); if (d0 == 0) n0 = __builtin_amdgcn_mfma_f32_32x32x16_bf16(b0, qr[0], negm, 0, 0, 0); else n0 = __builtin_amdgcn_mfma_f32_32x32x16_bf16(b0, qr[d0], n0, 0, 0, 0);
;     SBAR(); QF_CHUNK(2 * d0); SBAR();
;     if (d0 == 0) n1 = __builtin_amdgcn_mfma_f32_32x32x16_bf16(b1, qr[0], negm, 0, 0, 0); else n1 = __builtin_amdgcn_mfma_f32_32x32x16_bf16(b1, qr[d0], n1, 0, 0, 0);
;     SBAR(); QF_CHUNK(2 * d0 + 1); SBAR();
;     if (d0 == 7) { vf8_read<0>(vf0, vbv); SBAR(); } }
;     ...
;   psb += P1[15]; wd[3] = cvtpk(P1[14], P1[15]);
;   l_reg = l_reg * alpha + (psa + psb);
;   pa0 = *reinterpret_cast<bf16x8*>(&wa); pa1 = *reinterpret_cast<bf16x8*>(&wb); pa2 = *reinterpret_cast<bf16x8*>(&wc); pa3 = *reinterpret_cast<bf16x8*>(&wd);
; }
.LBB0_461:
	s_waitcnt lgkmcnt(0)
	ds_read_b128 v[204:207], v184 offset:16384
	ds_read_b128 v[208:211], v184 offset:24576
	ds_read_b128 v[248:251], v185 offset:16384
	ds_read_b128 v[252:255], v185 offset:24576
	v_add_u32_e32 v203, s96, v235
	s_waitcnt lgkmcnt(3)
	v_mfma_f32_32x32x16_bf16 v[114:129], v[204:207], v[152:155], v[66:81]
	v_exp_f32_e32 v98, v98
	s_waitcnt lgkmcnt(2)
	v_mfma_f32_32x32x16_bf16 v[82:97], v[208:211], v[152:155], v[66:81]
	v_exp_f32_e32 v99, v99
	v_add_f32_e32 v201, v133, v132
	v_cvt_pk_bf16_f32 v132, v132, v133
	ds_read_b128 v[204:207], v186 offset:16384
	ds_read_b128 v[208:211], v186 offset:24576
	s_waitcnt lgkmcnt(3)
	v_mfma_f32_32x32x16_bf16 v[114:129], v[248:251], v[160:163], v[114:129]
	v_exp_f32_e32 v100, v100
	v_add_f32_e32 v201, v134, v201
	v_add_f32_e32 v202, v98, v99
	s_waitcnt lgkmcnt(2)
	v_mfma_f32_32x32x16_bf16 v[82:97], v[252:255], v[160:163], v[82:97]
	v_exp_f32_e32 v101, v101
	v_add_f32_e32 v201, v135, v201
	v_add_f32_e32 v202, v202, v100
	v_cvt_pk_bf16_f32 v133, v134, v135
	v_cvt_pk_bf16_f32 v196, v98, v99
	ds_read_b128 v[248:251], v187 offset:16384
	ds_read_b128 v[252:255], v187 offset:24576
	s_waitcnt lgkmcnt(3)
	v_mfma_f32_32x32x16_bf16 v[114:129], v[204:207], v[148:151], v[114:129]
	v_exp_f32_e32 v102, v102
	v_add_f32_e32 v201, v136, v201
	v_add_f32_e32 v202, v202, v101
	s_waitcnt lgkmcnt(2)
	v_mfma_f32_32x32x16_bf16 v[82:97], v[208:211], v[148:151], v[82:97]
	v_exp_f32_e32 v103, v103
	v_add_f32_e32 v201, v137, v201
	v_add_f32_e32 v202, v202, v102
	v_cvt_pk_bf16_f32 v134, v136, v137
	v_cvt_pk_bf16_f32 v197, v100, v101
	ds_read_b128 v[204:207], v188 offset:16384
	ds_read_b128 v[208:211], v188 offset:24576
	s_waitcnt lgkmcnt(3)
	v_mfma_f32_32x32x16_bf16 v[114:129], v[248:251], v[156:159], v[114:129]
	v_exp_f32_e32 v104, v104
	v_add_f32_e32 v201, v138, v201
	v_add_f32_e32 v202, v202, v103
	s_waitcnt lgkmcnt(2)
	v_mfma_f32_32x32x16_bf16 v[82:97], v[252:255], v[156:159], v[82:97]
	v_exp_f32_e32 v105, v105
	v_add_f32_e32 v201, v139, v201
	v_add_f32_e32 v202, v202, v104
	v_cvt_pk_bf16_f32 v135, v138, v139
	v_cvt_pk_bf16_f32 v198, v102, v103
	ds_read_b128 v[248:251], v189 offset:16384
	ds_read_b128 v[252:255], v189 offset:24576
	s_waitcnt lgkmcnt(3)
	v_mfma_f32_32x32x16_bf16 v[114:129], v[204:207], v[168:171], v[114:129]
	v_exp_f32_e32 v106, v106
	v_add_f32_e32 v201, v140, v201
	v_add_f32_e32 v202, v202, v105
	s_waitcnt lgkmcnt(2)
	v_mfma_f32_32x32x16_bf16 v[82:97], v[208:211], v[168:171], v[82:97]
	v_exp_f32_e32 v107, v107
	v_add_f32_e32 v201, v141, v201
	v_add_f32_e32 v202, v202, v106
	v_cvt_pk_bf16_f32 v136, v140, v141
	v_cvt_pk_bf16_f32 v199, v104, v105
	ds_read_b128 v[204:207], v190 offset:16384
	ds_read_b128 v[208:211], v190 offset:24576
	s_waitcnt lgkmcnt(3)
	v_mfma_f32_32x32x16_bf16 v[114:129], v[248:251], v[176:179], v[114:129]
	v_exp_f32_e32 v108, v108
	v_add_f32_e32 v201, v142, v201
	v_add_f32_e32 v202, v202, v107
	s_waitcnt lgkmcnt(2)
	v_mfma_f32_32x32x16_bf16 v[82:97], v[252:255], v[176:179], v[82:97]
	v_exp_f32_e32 v109, v109
	v_add_f32_e32 v201, v143, v201
	v_add_f32_e32 v202, v202, v108
	v_cvt_pk_bf16_f32 v137, v142, v143
	v_cvt_pk_bf16_f32 v140, v106, v107
	ds_read_b128 v[248:251], v191 offset:16384
	ds_read_b128 v[252:255], v191 offset:24576
	s_waitcnt lgkmcnt(3)
	v_mfma_f32_32x32x16_bf16 v[114:129], v[204:207], v[164:167], v[114:129]
	v_exp_f32_e32 v110, v110
	v_add_f32_e32 v201, v144, v201
	v_add_f32_e32 v202, v202, v109
	s_waitcnt lgkmcnt(2)
	v_mfma_f32_32x32x16_bf16 v[82:97], v[208:211], v[164:167], v[82:97]
	v_exp_f32_e32 v111, v111
	v_add_f32_e32 v201, v145, v201
	v_add_f32_e32 v202, v202, v110
	v_cvt_pk_bf16_f32 v138, v144, v145
	v_cvt_pk_bf16_f32 v141, v108, v109
	s_waitcnt lgkmcnt(1)
	v_mfma_f32_32x32x16_bf16 v[114:129], v[248:251], v[172:175], v[114:129]
	v_exp_f32_e32 v112, v112
	v_add_f32_e32 v201, v146, v201
	v_add_f32_e32 v202, v202, v111
	s_waitcnt lgkmcnt(0)
	v_mfma_f32_32x32x16_bf16 v[82:97], v[252:255], v[172:175], v[82:97]
	v_exp_f32_e32 v113, v113
	v_add_f32_e32 v201, v147, v201
	v_add_f32_e32 v202, v202, v112
	v_cvt_pk_bf16_f32 v139, v146, v147
	v_cvt_pk_bf16_f32 v142, v110, v111
	ds_read_b64_tr_b16 v[144:145], v203 offset:0
	ds_read_b64_tr_b16 v[146:147], v203 offset:2048
	s_nop 0
	ds_read_b64_tr_b16 v[106:107], v203 offset:4096
	ds_read_b64_tr_b16 v[108:109], v203 offset:6144
	ds_read_b64_tr_b16 v[102:103], v203 offset:8192
	ds_read_b64_tr_b16 v[104:105], v203 offset:10240
	ds_read_b64_tr_b16 v[98:99], v203 offset:12288
	ds_read_b64_tr_b16 v[100:101], v203 offset:14336
	v_cvt_pk_bf16_f32 v143, v112, v113
	s_and_b64 vcc, exec, s[8:9]
	v_mov_b32_e32 v200, 1.0
	s_cbranch_vccnz .LBB0_463
	v_max_f32_e32 v110, v114, v115
	v_max3_f32 v110, v110, v116, v117
	v_max3_f32 v110, v110, v118, v119
	v_max3_f32 v110, v110, v120, v121
	v_max3_f32 v110, v110, v122, v123
	v_max3_f32 v110, v110, v124, v125
	v_max3_f32 v110, v110, v126, v127
	v_max3_f32 v110, v110, v128, v129
	v_max3_f32 v110, v110, v82, v83
	v_max3_f32 v110, v110, v84, v85
	v_max3_f32 v110, v110, v86, v87
	v_max3_f32 v110, v110, v88, v89
	v_max3_f32 v110, v110, v90, v91
	v_max3_f32 v110, v110, v92, v93
	v_max3_f32 v110, v110, v94, v95
	v_max3_f32 v110, v110, v96, v97
	v_mov_b32_e32 v111, v110
	s_nop 1
	v_permlane32_swap_b32_e32 v110, v111
	v_max_f32_e32 v110, v110, v111
	v_cmp_ge_f32_e32 vcc, s69, v110
	s_cmp_eq_u64 vcc, exec
	v_mov_b32_e32 v200, 1.0
	s_cbranch_scc0 .LBB0_469

; #define SBAR() __builtin_amdgcn_sched_barrier(0)
; __device__ __forceinline__ unsigned cvtpk(float lo, float hi) { unsigned r; asm volatile("v_cvt_pk_bf16_f32 %0, %1, %2" : "=v"(r) : "v"(lo), "v"(hi)); return r; }
; __device__ __forceinline__ void qkt_fin(f32x16& n0, f32x16& n1, const bf16_t* Ks, const bf16x8* qr, const f32x16& negm, int r32, int hi, ...
;   float psa = 0.f, psb = 0.f; u32x4 wa, wb, wc, wd;
;     ...
; #pragma unroll
;   for (int d0 = 0; d0 < 8; ++d0) { int cb = (d0 * 16 + hi * 8) * 2;
;     bf16x8 b0 = *reinterpret_cast<const bf16x8*>((const char*)Ks + KSWZ(r32, cb));
;     bf16x8 b1 = *reinterpret_cast<const bf16x8*>((const char*)Ks + KSWZ(32 + r32, cb));
;     SBAR(); if (d0 == 0) n0 = __builtin_amdgcn_mfma_f32_32x32x16_bf16(b0, qr[0], negm, 0, 0, 0); else n0 = __builtin_amdgcn_mfma_f32_32x32x16_bf16(b0, qr[d0], n0, 0, 0, 0);
;     SBAR(); QF_CHUNK(2 * d0); SBAR();
;     if (d0 == 0) n1 = __builtin_amdgcn_mfma_f32_32x32x16_bf16(b1, qr[0], negm, 0, 0, 0); else n1 = __builtin_amdgcn_mfma_f32_32x32x16_bf16(b1, qr[d0], n1, 0, 0, 0);
;     SBAR(); QF_CHUNK(2 * d0 + 1); SBAR();
;     if (d0 == 7) { vf8_read<0>(vf0, vbv); SBAR(); } }
;     ...
;   psb += P1[15]; wd[3] = cvtpk(P1[14], P1[15]);
;   l_reg = l_reg * alpha + (psa + psb);
;   pa0 = *reinterpret_cast<bf16x8*>(&wa); pa1 = *reinterpret_cast<bf16x8*>(&wb); pa2 = *reinterpret_cast<bf16x8*>(&wc); pa3 = *reinterpret_cast<bf16x8*>(&wd);
; }
.Lh2_453:
	s_setprio 1
	s_add_i32 s97, s96, 0xffff8000
	s_xor_b32 s98, s96, 0x10000
	s_add_i32 s99, s96, 0x8000
	s_and_b32 s99, s99, 0x18000
	ds_read_b128 v[98:101], v184 offset:49152
	ds_read_b128 v[196:199], v184 offset:57344
	v_xor_b32_e32 v184, 0x10000, v184
	ds_read_b128 v[248:251], v185 offset:49152
	ds_read_b128 v[252:255], v185 offset:57344
	v_xor_b32_e32 v185, 0x10000, v185
	v_add_u32_e32 v0, s97, v235
	s_waitcnt lgkmcnt(3)
	v_mfma_f32_32x32x16_bf16 v[132:147], v[98:101], v[152:155], v[66:81]
	v_exp_f32_e32 v82, v82
	s_waitcnt lgkmcnt(2)
	v_mfma_f32_32x32x16_bf16 v[98:113], v[196:199], v[152:155], v[66:81]
	v_exp_f32_e32 v83, v83
	v_add_f32_e32 v245, v115, v114
	v_cvt_pk_bf16_f32 v196, v114, v115
	ds_read_b128 v[202:205], v186 offset:49152
	ds_read_b128 v[206:209], v186 offset:57344
	v_xor_b32_e32 v186, 0x10000, v186
	s_waitcnt lgkmcnt(3)
	v_mfma_f32_32x32x16_bf16 v[132:147], v[248:251], v[160:163], v[132:147]
	v_exp_f32_e32 v84, v84
	v_add_f32_e32 v245, v116, v245
	v_add_f32_e32 v246, v82, v83
	s_waitcnt lgkmcnt(2)
	v_mfma_f32_32x32x16_bf16 v[98:113], v[252:255], v[160:163], v[98:113]
	v_exp_f32_e32 v85, v85
	v_add_f32_e32 v245, v117, v245
	v_add_f32_e32 v246, v246, v84
	v_cvt_pk_bf16_f32 v197, v116, v117
	v_cvt_pk_bf16_f32 v200, v82, v83
	ds_read_b128 v[248:251], v187 offset:49152
	ds_read_b128 v[252:255], v187 offset:57344
	v_xor_b32_e32 v187, 0x10000, v187
	s_add_i32 s79, s99, s100
	s_add_i32 m0, s79, 0x4000
	s_add_i32 s79, s79, 0x6000
	global_load_lds_dwordx4 v180, s[82:83]
	s_waitcnt lgkmcnt(3)
	v_mfma_f32_32x32x16_bf16 v[132:147], v[202:205], v[148:151], v[132:147]
	v_exp_f32_e32 v86, v86
	v_add_f32_e32 v245, v118, v245
	v_add_f32_e32 v246, v246, v85
	s_waitcnt lgkmcnt(2)
	v_mfma_f32_32x32x16_bf16 v[98:113], v[206:209], v[148:151], v[98:113]
	v_exp_f32_e32 v87, v87
	v_add_f32_e32 v245, v119, v245
	v_add_f32_e32 v246, v246, v86
	v_cvt_pk_bf16_f32 v198, v118, v119
	v_cvt_pk_bf16_f32 v201, v84, v85
	ds_read_b128 v[204:207], v188 offset:49152
	ds_read_b128 v[208:211], v188 offset:57344
	v_xor_b32_e32 v188, 0x10000, v188
	s_mov_b32 m0, s79
	s_add_i32 s79, s99, s101
	global_load_lds_dwordx4 v182, s[82:83]
	s_waitcnt lgkmcnt(3)
	v_mfma_f32_32x32x16_bf16 v[132:147], v[248:251], v[156:159], v[132:147]
	v_exp_f32_e32 v88, v88
	v_add_f32_e32 v245, v120, v245
	v_add_f32_e32 v246, v246, v87
	s_waitcnt lgkmcnt(2)
	v_mfma_f32_32x32x16_bf16 v[98:113], v[252:255], v[156:159], v[98:113]
	v_exp_f32_e32 v89, v89
	v_add_f32_e32 v245, v121, v245
	v_add_f32_e32 v246, v246, v88
	v_cvt_pk_bf16_f32 v199, v120, v121
	v_cvt_pk_bf16_f32 v202, v86, v87
	ds_read_b128 v[248:251], v189 offset:49152
	ds_read_b128 v[252:255], v189 offset:57344
	v_xor_b32_e32 v189, 0x10000, v189
	s_mov_b32 m0, s79
	s_add_i32 s79, s79, 0x380
	global_load_lds_dwordx4 v214, s[82:83]
	s_waitcnt lgkmcnt(3)
	v_mfma_f32_32x32x16_bf16 v[132:147], v[204:207], v[168:171], v[132:147]
	v_exp_f32_e32 v90, v90
	v_add_f32_e32 v245, v122, v245
	v_add_f32_e32 v246, v246, v89
	s_waitcnt lgkmcnt(2)
	v_mfma_f32_32x32x16_bf16 v[98:113], v[208:211], v[168:171], v[98:113]
	v_exp_f32_e32 v91, v91
	v_add_f32_e32 v245, v123, v245
	v_add_f32_e32 v246, v246, v90
	v_cvt_pk_bf16_f32 v204, v122, v123
	v_cvt_pk_bf16_f32 v203, v88, v89
	ds_read_b128 v[114:117], v190 offset:49152
	ds_read_b128 v[118:121], v190 offset:57344
	v_xor_b32_e32 v190, 0x10000, v190
	s_mov_b32 m0, s79
	s_nop 0
	global_load_lds_dwordx4 v214, s[82:83] offset:128
	s_add_u32 s82, s82, s76
	s_addc_u32 s83, s83, s77
	s_waitcnt lgkmcnt(3)
	v_mfma_f32_32x32x16_bf16 v[132:147], v[248:251], v[176:179], v[132:147]
	v_exp_f32_e32 v92, v92
	v_add_f32_e32 v245, v124, v245
	v_add_f32_e32 v246, v246, v91
	s_waitcnt lgkmcnt(2)
	v_mfma_f32_32x32x16_bf16 v[98:113], v[252:255], v[176:179], v[98:113]
	v_exp_f32_e32 v93, v93
	v_add_f32_e32 v245, v125, v245
	v_add_f32_e32 v246, v246, v92
	v_cvt_pk_bf16_f32 v205, v124, v125
	v_cvt_pk_bf16_f32 v208, v90, v91
	ds_read_b128 v[248:251], v191 offset:49152
	ds_read_b128 v[252:255], v191 offset:57344
	v_xor_b32_e32 v191, 0x10000, v191
	s_waitcnt lgkmcnt(3)
	v_mfma_f32_32x32x16_bf16 v[132:147], v[114:117], v[164:167], v[132:147]
	v_exp_f32_e32 v94, v94
	v_add_f32_e32 v245, v126, v245
	v_add_f32_e32 v246, v246, v93
	s_waitcnt lgkmcnt(2)
	v_mfma_f32_32x32x16_bf16 v[98:113], v[118:121], v[164:167], v[98:113]
	v_exp_f32_e32 v95, v95
	v_add_f32_e32 v245, v127, v245
	v_add_f32_e32 v246, v246, v94
	v_cvt_pk_bf16_f32 v206, v126, v127
	v_cvt_pk_bf16_f32 v209, v92, v93
	s_waitcnt lgkmcnt(1)
	v_mfma_f32_32x32x16_bf16 v[132:147], v[248:251], v[172:175], v[132:147]
	v_exp_f32_e32 v96, v96
	v_add_f32_e32 v245, v128, v245
	v_add_f32_e32 v246, v246, v95
	s_waitcnt lgkmcnt(0)
	v_mfma_f32_32x32x16_bf16 v[98:113], v[252:255], v[172:175], v[98:113]
	v_exp_f32_e32 v97, v97
	v_add_f32_e32 v245, v129, v245
	v_add_f32_e32 v246, v246, v96
	v_cvt_pk_bf16_f32 v207, v128, v129
	v_cvt_pk_bf16_f32 v210, v94, v95
	v_mov_b32_e32 v131, v97
	v_cvt_pk_bf16_f32 v211, v96, v97
	ds_read_b64_tr_b16 v[94:95], v0 offset:0
	ds_read_b64_tr_b16 v[96:97], v0 offset:2048
	ds_read_b64_tr_b16 v[90:91], v0 offset:4096
	ds_read_b64_tr_b16 v[92:93], v0 offset:6144
	ds_read_b64_tr_b16 v[86:87], v0 offset:8192
	ds_read_b64_tr_b16 v[88:89], v0 offset:10240
	ds_read_b64_tr_b16 v[82:83], v0 offset:12288
	ds_read_b64_tr_b16 v[84:85], v0 offset:14336
	s_andn2_b64 s[8:9], exec, s[0:1]
	s_andn2_b64 vcc, exec, s[0:1]
	s_cbranch_vccnz .Lh2_456
; template <bool FIRST, bool DOEXP = true>
; __device__ __forceinline__ void partialSM(f32x16& p0, f32x16& p1, float& m_reg, f32x16& negm, float& alpha, const bool track = true) {
;     ...
;   float pmax = p0[0];
; #pragma unroll
;   for (int r = 1; r < 16; ++r) pmax = fmaxf(pmax, p0[r]);
; #pragma unroll
;   for (int r = 0; r < 16; ++r) pmax = fmaxf(pmax, p1[r]);
;   { auto rr = __builtin_amdgcn_permlane32_swap(__float_as_uint(pmax), __float_as_uint(pmax), false, false);
;     pmax = fmaxf(__uint_as_float(rr[0]), __uint_as_float(rr[1])); }
;   if (!FIRST && __builtin_expect(__all(pmax <= THRL), 1)) { alpha = 1.f; }
;   else { const float dl = FIRST ? pmax : fmaxf(pmax, 0.f); m_reg += dl; alpha = FIRST ? 1.f : __builtin_amdgcn_exp2f(-dl);
; #pragma unroll
;     for (int r = 0; r < 16; ++r) { p0[r] -= dl; p1[r] -= dl; }
; #pragma unroll
;     for (int r = 0; r < 16; ++r) negm[r] = -m_reg;
;     asm volatile("" : "+v"(negm)); }
	v_max_f32_e32 v114, v132, v133
	v_max3_f32 v114, v114, v134, v135
	v_max3_f32 v114, v114, v136, v137
	v_max3_f32 v114, v114, v138, v139
	v_max3_f32 v114, v114, v140, v141
	v_max3_f32 v114, v114, v142, v143
	v_max3_f32 v114, v114, v144, v145
	v_max3_f32 v114, v114, v146, v147
	v_max3_f32 v114, v114, v98, v99
	v_max3_f32 v114, v114, v100, v101
	v_max3_f32 v114, v114, v102, v103
	v_max3_f32 v114, v114, v104, v105
	v_max3_f32 v114, v114, v106, v107
	v_max3_f32 v114, v114, v108, v109
	v_max3_f32 v114, v114, v110, v111
	v_max3_f32 v114, v114, v112, v113
	v_mov_b32_e32 v115, v114
	s_nop 1
	v_permlane32_swap_b32_e32 v114, v115
	v_max_f32_e32 v114, v114, v115
	v_cmp_ge_f32_e32 vcc, s69, v114
	s_cmp_eq_u64 vcc, exec
	v_mov_b32_e32 v130, 1.0
	s_cbranch_scc1 .Lh2_457
	v_max_f32_e32 v66, v114, v114
	v_max_f32_e32 v66, 0, v66
	v_exp_f32_e64 v130, -v66
	v_add_f32_e32 v222, v222, v66
	v_sub_f32_e32 v147, v147, v66
	v_sub_f32_e32 v146, v146, v66
	v_sub_f32_e32 v145, v145, v66
	v_sub_f32_e32 v144, v144, v66
	v_sub_f32_e32 v143, v143, v66
	v_sub_f32_e32 v142, v142, v66
	v_sub_f32_e32 v141, v141, v66
	v_sub_f32_e32 v140, v140, v66
	v_sub_f32_e32 v139, v139, v66
	v_sub_f32_e32 v138, v138, v66
	v_sub_f32_e32 v137, v137, v66
	v_sub_f32_e32 v136, v136, v66
	v_sub_f32_e32 v135, v135, v66
	v_sub_f32_e32 v134, v134, v66
	v_sub_f32_e32 v133, v133, v66
	v_sub_f32_e32 v132, v132, v66
	v_sub_f32_e32 v113, v113, v66
	v_sub_f32_e32 v112, v112, v66
	v_sub_f32_e32 v111, v111, v66
	v_sub_f32_e32 v110, v110, v66
	v_sub_f32_e32 v109, v109, v66
	v_sub_f32_e32 v108, v108, v66
	v_sub_f32_e32 v107, v107, v66
	v_sub_f32_e32 v106, v106, v66
	v_sub_f32_e32 v105, v105, v66
	v_sub_f32_e32 v104, v104, v66
	v_sub_f32_e32 v103, v103, v66
	v_sub_f32_e32 v102, v102, v66
	v_sub_f32_e32 v101, v101, v66
	v_sub_f32_e32 v100, v100, v66
	v_sub_f32_e32 v99, v99, v66
	v_sub_f32_e32 v98, v98, v66
	v_xor_b32_e32 v66, 0x80000000, v222
	v_mov_b32_e32 v67, v66
	v_mov_b32_e32 v68, v66
	v_mov_b32_e32 v69, v66
	v_mov_b32_e32 v70, v66
	v_mov_b32_e32 v71, v66
	v_mov_b32_e32 v72, v66
	v_mov_b32_e32 v73, v66
	v_mov_b32_e32 v74, v66
	v_mov_b32_e32 v75, v66
	v_mov_b32_e32 v76, v66
	v_mov_b32_e32 v77, v66
	v_mov_b32_e32 v78, v66
	v_mov_b32_e32 v79, v66
	v_mov_b32_e32 v80, v66
	v_mov_b32_e32 v81, v66
	s_branch .Lh2_457

; #define SBAR() __builtin_amdgcn_sched_barrier(0)
; __device__ __forceinline__ unsigned cvtpk(float lo, float hi) { unsigned r; asm volatile("v_cvt_pk_bf16_f32 %0, %1, %2" : "=v"(r) : "v"(lo), "v"(hi)); return r; }
; __device__ __forceinline__ void qkt_fin(f32x16& n0, f32x16& n1, const bf16_t* Ks, const bf16x8* qr, const f32x16& negm, int r32, int hi, ...
;   float psa = 0.f, psb = 0.f; u32x4 wa, wb, wc, wd;
;     ...
; #pragma unroll
;   for (int d0 = 0; d0 < 8; ++d0) { int cb = (d0 * 16 + hi * 8) * 2;
;     bf16x8 b0 = *reinterpret_cast<const bf16x8*>((const char*)Ks + KSWZ(r32, cb));
;     bf16x8 b1 = *reinterpret_cast<const bf16x8*>((const char*)Ks + KSWZ(32 + r32, cb));
;     SBAR(); if (d0 == 0) n0 = __builtin_amdgcn_mfma_f32_32x32x16_bf16(b0, qr[0], negm, 0, 0, 0); else n0 = __builtin_amdgcn_mfma_f32_32x32x16_bf16(b0, qr[d0], n0, 0, 0, 0);
;     SBAR(); QF_CHUNK(2 * d0); SBAR();
;     if (d0 == 0) n1 = __builtin_amdgcn_mfma_f32_32x32x16_bf16(b1, qr[0], negm, 0, 0, 0); else n1 = __builtin_amdgcn_mfma_f32_32x32x16_bf16(b1, qr[d0], n1, 0, 0, 0);
;     SBAR(); QF_CHUNK(2 * d0 + 1); SBAR();
;     if (d0 == 7) { vf8_read<0>(vf0, vbv); SBAR(); } }
;     ...
;   psb += P1[15]; wd[3] = cvtpk(P1[14], P1[15]);
;   l_reg = l_reg * alpha + (psa + psb);
;   pa0 = *reinterpret_cast<bf16x8*>(&wa); pa1 = *reinterpret_cast<bf16x8*>(&wb); pa2 = *reinterpret_cast<bf16x8*>(&wc); pa3 = *reinterpret_cast<bf16x8*>(&wd);
; }
.Lh2_461:
	s_setprio 1
	s_waitcnt lgkmcnt(0)
	s_waitcnt vmcnt(0)
	s_barrier
	ds_read_b128 v[204:207], v184 offset:16384
	ds_read_b128 v[208:211], v184 offset:24576
	ds_read_b128 v[248:251], v185 offset:16384
	ds_read_b128 v[252:255], v185 offset:24576
	v_add_u32_e32 v203, s96, v235
	s_waitcnt lgkmcnt(3)
	v_mfma_f32_32x32x16_bf16 v[114:129], v[204:207], v[152:155], v[66:81]
	v_exp_f32_e32 v98, v98
	s_waitcnt lgkmcnt(2)
	v_mfma_f32_32x32x16_bf16 v[82:97], v[208:211], v[152:155], v[66:81]
	v_exp_f32_e32 v99, v99
	v_add_f32_e32 v201, v133, v132
	v_cvt_pk_bf16_f32 v132, v132, v133
	ds_read_b128 v[204:207], v186 offset:16384
	ds_read_b128 v[208:211], v186 offset:24576
	s_waitcnt lgkmcnt(3)
	v_mfma_f32_32x32x16_bf16 v[114:129], v[248:251], v[160:163], v[114:129]
	v_exp_f32_e32 v100, v100
	v_add_f32_e32 v201, v134, v201
	v_add_f32_e32 v202, v98, v99
	s_waitcnt lgkmcnt(2)
	v_mfma_f32_32x32x16_bf16 v[82:97], v[252:255], v[160:163], v[82:97]
	v_exp_f32_e32 v101, v101
	v_add_f32_e32 v201, v135, v201
	v_add_f32_e32 v202, v202, v100
	v_cvt_pk_bf16_f32 v133, v134, v135
	v_cvt_pk_bf16_f32 v196, v98, v99
	ds_read_b128 v[248:251], v187 offset:16384
	ds_read_b128 v[252:255], v187 offset:24576
	s_add_i32 s79, s98, s100
	s_add_i32 m0, s79, 0x4000
	s_add_i32 s79, s79, 0x6000
	global_load_lds_dwordx4 v180, s[82:83]
	s_waitcnt lgkmcnt(3)
	v_mfma_f32_32x32x16_bf16 v[114:129], v[204:207], v[148:151], v[114:129]
	v_exp_f32_e32 v102, v102
	v_add_f32_e32 v201, v136, v201
	v_add_f32_e32 v202, v202, v101
	s_waitcnt lgkmcnt(2)
	v_mfma_f32_32x32x16_bf16 v[82:97], v[208:211], v[148:151], v[82:97]
	v_exp_f32_e32 v103, v103
	v_add_f32_e32 v201, v137, v201
	v_add_f32_e32 v202, v202, v102
	v_cvt_pk_bf16_f32 v134, v136, v137
	v_cvt_pk_bf16_f32 v197, v100, v101
	ds_read_b128 v[204:207], v188 offset:16384
	ds_read_b128 v[208:211], v188 offset:24576
	s_mov_b32 m0, s79
	s_add_i32 s79, s98, s101
	global_load_lds_dwordx4 v182, s[82:83]
	s_waitcnt lgkmcnt(3)
	v_mfma_f32_32x32x16_bf16 v[114:129], v[248:251], v[156:159], v[114:129]
	v_exp_f32_e32 v104, v104
	v_add_f32_e32 v201, v138, v201
	v_add_f32_e32 v202, v202, v103
	s_waitcnt lgkmcnt(2)
	v_mfma_f32_32x32x16_bf16 v[82:97], v[252:255], v[156:159], v[82:97]
	v_exp_f32_e32 v105, v105
	v_add_f32_e32 v201, v139, v201
	v_add_f32_e32 v202, v202, v104
	v_cvt_pk_bf16_f32 v135, v138, v139
	v_cvt_pk_bf16_f32 v198, v102, v103
	ds_read_b128 v[248:251], v189 offset:16384
	ds_read_b128 v[252:255], v189 offset:24576
	s_mov_b32 m0, s79
	s_add_i32 s79, s79, 0x380
	global_load_lds_dwordx4 v214, s[82:83]
	s_waitcnt lgkmcnt(3)
	v_mfma_f32_32x32x16_bf16 v[114:129], v[204:207], v[168:171], v[114:129]
	v_exp_f32_e32 v106, v106
	v_add_f32_e32 v201, v140, v201
	v_add_f32_e32 v202, v202, v105
	s_waitcnt lgkmcnt(2)
	v_mfma_f32_32x32x16_bf16 v[82:97], v[208:211], v[168:171], v[82:97]
	v_exp_f32_e32 v107, v107
	v_add_f32_e32 v201, v141, v201
	v_add_f32_e32 v202, v202, v106
	v_cvt_pk_bf16_f32 v136, v140, v141
	v_cvt_pk_bf16_f32 v199, v104, v105
	ds_read_b128 v[204:207], v190 offset:16384
	ds_read_b128 v[208:211], v190 offset:24576
	s_mov_b32 m0, s79
	s_nop 0
	global_load_lds_dwordx4 v214, s[82:83] offset:128
	s_add_u32 s82, s82, s76
	s_addc_u32 s83, s83, s77
	s_waitcnt lgkmcnt(3)
	v_mfma_f32_32x32x16_bf16 v[114:129], v[248:251], v[176:179], v[114:129]
	v_exp_f32_e32 v108, v108
	v_add_f32_e32 v201, v142, v201
	v_add_f32_e32 v202, v202, v107
	s_waitcnt lgkmcnt(2)
	v_mfma_f32_32x32x16_bf16 v[82:97], v[252:255], v[176:179], v[82:97]
	v_exp_f32_e32 v109, v109
	v_add_f32_e32 v201, v143, v201
	v_add_f32_e32 v202, v202, v108
	v_cvt_pk_bf16_f32 v137, v142, v143
	v_cvt_pk_bf16_f32 v140, v106, v107
	ds_read_b128 v[248:251], v191 offset:16384
	ds_read_b128 v[252:255], v191 offset:24576
	s_waitcnt lgkmcnt(3)
	v_mfma_f32_32x32x16_bf16 v[114:129], v[204:207], v[164:167], v[114:129]
	v_exp_f32_e32 v110, v110
	v_add_f32_e32 v201, v144, v201
	v_add_f32_e32 v202, v202, v109
	s_waitcnt lgkmcnt(2)
	v_mfma_f32_32x32x16_bf16 v[82:97], v[208:211], v[164:167], v[82:97]
	v_exp_f32_e32 v111, v111
	v_add_f32_e32 v201, v145, v201
	v_add_f32_e32 v202, v202, v110
	v_cvt_pk_bf16_f32 v138, v144, v145
	v_cvt_pk_bf16_f32 v141, v108, v109
	s_waitcnt lgkmcnt(1)
	v_mfma_f32_32x32x16_bf16 v[114:129], v[248:251], v[172:175], v[114:129]
	v_exp_f32_e32 v112, v112
	v_add_f32_e32 v201, v146, v201
	v_add_f32_e32 v202, v202, v111
	s_waitcnt lgkmcnt(0)
	v_mfma_f32_32x32x16_bf16 v[82:97], v[252:255], v[172:175], v[82:97]
	v_exp_f32_e32 v113, v113
	v_add_f32_e32 v201, v147, v201
	v_add_f32_e32 v202, v202, v112
	v_cvt_pk_bf16_f32 v139, v146, v147
	v_cvt_pk_bf16_f32 v142, v110, v111
	ds_read_b64_tr_b16 v[144:145], v203 offset:0
	ds_read_b64_tr_b16 v[146:147], v203 offset:2048
	s_nop 0
	ds_read_b64_tr_b16 v[106:107], v203 offset:4096
	ds_read_b64_tr_b16 v[108:109], v203 offset:6144
	ds_read_b64_tr_b16 v[102:103], v203 offset:8192
	ds_read_b64_tr_b16 v[104:105], v203 offset:10240
	ds_read_b64_tr_b16 v[98:99], v203 offset:12288
	ds_read_b64_tr_b16 v[100:101], v203 offset:14336
	v_cvt_pk_bf16_f32 v143, v112, v113
	s_and_b64 vcc, exec, s[8:9]
	v_mov_b32_e32 v200, 1.0
	s_cbranch_vccnz .Lh2_463
	v_max_f32_e32 v110, v114, v115
	v_max3_f32 v110, v110, v116, v117
	v_max3_f32 v110, v110, v118, v119
	v_max3_f32 v110, v110, v120, v121
	v_max3_f32 v110, v110, v122, v123
	v_max3_f32 v110, v110, v124, v125
	v_max3_f32 v110, v110, v126, v127
	v_max3_f32 v110, v110, v128, v129
	v_max3_f32 v110, v110, v82, v83
	v_max3_f32 v110, v110, v84, v85
	v_max3_f32 v110, v110, v86, v87
	v_max3_f32 v110, v110, v88, v89
	v_max3_f32 v110, v110, v90, v91
	v_max3_f32 v110, v110, v92, v93
	v_max3_f32 v110, v110, v94, v95
	v_max3_f32 v110, v110, v96, v97
	v_mov_b32_e32 v111, v110
	s_nop 1
	v_permlane32_swap_b32_e32 v110, v111
	v_max_f32_e32 v110, v110, v111
	v_cmp_ge_f32_e32 vcc, s69, v110
	s_cmp_eq_u64 vcc, exec
	v_mov_b32_e32 v200, 1.0
	s_cbranch_scc0 .Lh2_469
